# P0 de-phasing: workgroups >= 32 (four row trips, one trip of slack) with bit 3 set start the row loop 4.7 us later
# baseline (speedup 1.0000x reference)
.LBB0_16:
	v_writelane_b32 v254, s12, 4
	s_nop 1
	v_writelane_b32 v254, s13, 5
	v_writelane_b32 v254, s14, 6
	v_writelane_b32 v254, s15, 7
	v_writelane_b32 v254, s16, 8
	v_writelane_b32 v254, s17, 9
	v_writelane_b32 v254, s18, 10
	v_writelane_b32 v254, s19, 11
	v_writelane_b32 v254, s20, 12
	v_writelane_b32 v254, s21, 13
	v_writelane_b32 v254, s22, 14
	v_writelane_b32 v254, s23, 15
	v_writelane_b32 v254, s24, 16
	v_writelane_b32 v254, s25, 17
	v_writelane_b32 v254, s26, 18
	v_writelane_b32 v254, s27, 19
	s_or_b64 exec, exec, s[0:1]
	s_load_dwordx16 s[64:79], s[80:81], 0x0
	s_load_dwordx16 s[40:55], s[80:81], 0x80
	v_lshrrev_b32_e32 v1, 6, v0
	v_lshl_or_b32 v198, s59, 3, v1
	s_movk_i32 s26, 0x4100
	v_cmp_gt_i32_e32 vcc, s26, v198
	v_mbcnt_lo_u32_b32 v1, -1, 0
	s_waitcnt lgkmcnt(0)
	s_barrier
	s_and_saveexec_b64 s[0:1], vcc
	s_cbranch_execz .LBB0_55
	s_cmp_lt_u32 s59, 32
	s_cbranch_scc1 .Lstg0_done
	s_bitcmp0_b32 s59, 3
	s_cbranch_scc1 .Lstg0_done
	s_sleep 127
	s_sleep 50
.Lstg0_done:
	v_mbcnt_hi_u32_b32 v22, -1, v1
	v_and_b32_e32 v10, 64, v22
	v_add_u32_e32 v23, 64, v10
	v_xor_b32_e32 v10, 32, v22
	v_cmp_lt_i32_e32 vcc, v10, v23
	s_load_dwordx16 s[8:23], s[80:81], 0x40
	v_and_b32_e32 v21, 63, v0
	v_cndmask_b32_e32 v10, v22, v10, vcc
	v_lshlrev_b32_e32 v90, 2, v10
	v_xor_b32_e32 v10, 16, v22
	v_cmp_lt_i32_e32 vcc, v10, v23
	v_lshlrev_b32_e32 v24, 4, v21
	s_waitcnt lgkmcnt(0)
	global_load_dwordx4 v[2:5], v24, s[8:9]
	global_load_dwordx4 v[6:9], v24, s[8:9] offset:1024
	v_cndmask_b32_e32 v10, v22, v10, vcc
	v_lshlrev_b32_e32 v91, 2, v10
	v_xor_b32_e32 v10, 8, v22
	v_cmp_lt_i32_e32 vcc, v10, v23
	v_xor_b32_e32 v25, 4, v22
	v_mov_b32_e32 v47, 0
	v_cndmask_b32_e32 v10, v22, v10, vcc
	v_lshlrev_b32_e32 v92, 2, v10
	global_load_dwordx4 v[10:13], v24, s[8:9] offset:2048
	global_load_dwordx4 v[14:17], v24, s[8:9] offset:3072
	v_cmp_lt_i32_e32 vcc, v25, v23
	v_lshlrev_b32_e32 v46, 3, v21
	s_mov_b64 s[2:3], 0x1e6ea00
	v_cndmask_b32_e32 v25, v22, v25, vcc
	v_lshlrev_b32_e32 v93, 2, v25
	v_xor_b32_e32 v25, 2, v22
	v_cmp_lt_i32_e32 vcc, v25, v23
	v_add_u32_e32 v96, 16, v24
	v_mov_b32_e32 v53, v47
	v_cndmask_b32_e32 v25, v22, v25, vcc
	v_lshlrev_b32_e32 v94, 2, v25
	v_xor_b32_e32 v25, 1, v22
	v_cmp_lt_i32_e32 vcc, v25, v23
	s_mov_b64 s[14:15], 0x1880000
	v_ashrrev_i32_e32 v199, 31, v198
	v_cndmask_b32_e32 v22, v22, v25, vcc
	v_lshlrev_b32_e32 v95, 2, v22
	v_lshl_add_u64 v[22:23], s[90:91], 0, v[46:47]
	v_lshl_add_u64 v[50:51], v[22:23], 0, s[2:3]
	v_bfe_u32 v22, v0, 2, 4
	v_subrev_co_u32_e32 v52, vcc, 8, v22
	v_lshlrev_b32_e32 v22, 2, v22
	v_mov_b32_e32 v23, v47
	v_lshl_add_u64 v[24:25], s[90:91], 0, v[22:23]
	v_lshlrev_b32_e32 v20, 2, v21
	v_lshlrev_b32_e32 v48, 3, v19
	v_cmp_gt_u32_e64 s[2:3], 32, v21
	v_and_b32_e32 v21, 16, v0
	v_cmp_eq_u32_e64 s[12:13], 0, v18
	v_lshl_add_u64 v[54:55], v[24:25], 0, s[14:15]
	v_lshlrev_b32_e32 v56, 4, v19
	v_lshlrev_b64 v[18:19], 2, v[52:53]
	v_lshlrev_b64 v[24:25], 5, v[198:199]
	v_cmp_eq_u32_e64 s[6:7], 0, v21
	v_and_b32_e32 v21, 8, v0
	v_lshl_add_u64 v[58:59], s[40:41], 0, v[18:19]
	v_lshl_add_u64 v[60:61], s[16:17], 0, v[22:23]
	v_lshl_add_u64 v[22:23], v[24:25], 0, v[22:23]
	v_lshl_add_u64 v[18:19], v[24:25], 0, v[18:19]
	v_cmp_eq_u32_e64 s[8:9], 0, v21
	v_and_b32_e32 v21, 4, v0
	v_ashrrev_i32_e32 v57, 31, v56
	v_lshl_add_u64 v[62:63], v[22:23], 0, s[14:15]
	v_lshl_add_u64 v[18:19], s[88:89], 0, v[18:19]
	s_mov_b64 s[14:15], 0x8100000
	v_lshlrev_b64 v[68:69], 11, v[198:199]
	v_add_u32_e32 v97, 0x8000, v96
	v_cmp_eq_u32_e64 s[10:11], 0, v21
	s_xor_b64 s[4:5], vcc, -1
	v_lshlrev_b64 v[64:65], 5, v[56:57]
	v_lshl_add_u64 v[66:67], v[18:19], 0, s[14:15]
	v_or_b32_e32 v68, v68, v46
	v_lshlrev_b64 v[70:71], 11, v[56:57]
	v_mov_b32_e32 v49, v47
	s_mov_b64 s[18:19], 0
	s_movk_i32 s27, 0x40ff
	s_movk_i32 s28, 0x3fff
	s_movk_i32 s29, 0x4000
	v_lshlrev_b32_e32 v72, 2, v20
	v_mov_b32_e32 v98, 0x358637bd
	s_mov_b32 s30, 0x800000
	s_mov_b32 s31, 0xc1a00000
	s_mov_b32 s33, 0xbfb8aa3b
	s_mov_b32 s34, 0x42ce8ed0
	s_mov_b32 s35, 0xc2b17218
	s_mov_b32 s36, 0x7f800000
	s_mov_b32 s37, 0x3f2aaaab
	v_mov_b32_e32 v99, 0x3ecc95a3
	s_mov_b32 s38, 0x3f317218
	s_mov_b32 s39, 0x33800000
	s_mov_b32 s40, 0x41a00000
	s_mov_b32 s41, 0x3fb8aa3b
	s_mov_b32 s56, 0xc2ce8ed0
	s_mov_b32 s57, 0x42b17218
	v_mov_b32_e32 v100, 0x7f800000
	v_mov_b32_e32 v74, 0x3f317218
	v_mov_b64_e32 v[76:77], v[198:199]
	s_branch .LBB0_20
